# P7 start stagger in 8 groups (bi&7) x 1 sleep
# speedup vs baseline: 1.0251x; 1.0092x over previous
.LBB0_295:
	s_nop 0
	v_readlane_b32 s0, v254, 37
	v_readlane_b32 s1, v254, 38
	s_and_b64 vcc, exec, s[0:1]
	s_cbranch_vccz .LBB0_316
	s_mov_b32 s36, s35
	s_mov_b32 s0, s98
	s_mov_b32 s1, -1
	v_mbcnt_lo_u32_b32 v0, -1, 0
	v_mbcnt_hi_u32_b32 v0, s1, v0
	v_readlane_b32 s1, v252, 0
	v_lshl_add_u32 v158, s0, 6, v0
	s_mov_b32 s4, s1
	s_ashr_i32 s0, s1, 3
	v_readlane_b32 s5, v254, 6
	s_cmp_ge_i32 s0, s5
	s_cbranch_scc1 .LBB0_315
	s_cmpk_gt_i32 s0, 0x9f
	s_cbranch_scc1 .LBB0_315
	s_and_b32 s6, s0, 7
.Lp7_stag_loop:
	s_cmp_eq_u32 s6, 0
	s_cbranch_scc1 .Lp7_nostag
	s_sleep 127
	s_add_i32 s6, s6, -1
	s_branch .Lp7_stag_loop
